# OUT-projection GEMM epilogue: skip store-draining vmcnt waits on the bf16-residual path (layers>0), wait only where pipelined residual loads are consumed
# baseline (speedup 1.0000x reference)
; __device__ __forceinline__ float bflo(unsigned w) { return __uint_as_float(w << 16); }
; __device__ __forceinline__ float bfhi(unsigned w) { return __uint_as_float(w & 0xffff0000u); }
;   __device__ __forceinline__ void operator()(const f32x4 (&acc)[2][2][4][2], const Unit& u, int wr, int wc, int fr, int fq) const {
;     ...
;         for (int bj = 0; bj < 2; ++bj) {
;           float x[8], rr[8];
;           if (first) {
;             const float* rp = resid_row(*p, true, row) + col0;
;             const float4 r0 = *(const float4*)(rp + bj * PG_HALF), r1 = *(const float4*)(rp + bj * PG_HALF + 4);
;             rr[0] = r0.x; rr[1] = r0.y; rr[2] = r0.z; rr[3] = r0.w; rr[4] = r1.x; rr[5] = r1.y; rr[6] = r1.z; rr[7] = r1.w;
;           } else {
;             const u32x4 rw = rwq[aim][m - mb][bj];
; #pragma unroll
;             for (int q = 0; q < 4; ++q) { rr[q * 2] = bflo(rw[q]); rr[q * 2 + 1] = bfhi(rw[q]); }
;           }
; #pragma unroll
;           for (int n = 0; n < 2; ++n) {
;             const float4 g = gq[bj][n];
;             const f32x4 a = acc[ai][bj][m][n];
;             x[n * 4 + 0] = rr[n * 4 + 0] + g.x * a[0]; x[n * 4 + 1] = rr[n * 4 + 1] + g.y * a[1]; x[n * 4 + 2] = rr[n * 4 + 2] + g.z * a[2]; x[n * 4 + 3] = rr[n * 4 + 3] + g.w * a[3];
;           }
;           { u32x4 xw = {cvtpk(x[0], x[1]), cvtpk(x[2], x[3]), cvtpk(x[4], x[5]), cvtpk(x[6], x[7])}; *(u32x4*)(op + bj * PG_HALF) = xw; }
.LBB0_515:
	v_lshlrev_b64 v[198:199], 11, v[222:223]
	v_lshl_add_u64 v[232:233], s[86:87], 0, v[198:199]
	v_lshlrev_b64 v[196:197], 1, v[220:221]
	v_lshl_add_u64 v[232:233], v[232:233], 0, v[196:197]
	s_cmp_lg_u64 s[82:83], 0
	s_cbranch_scc1 .Lepw_1
	s_waitcnt vmcnt(0)
.Lepw_1:
	v_fmac_f32_e32 v192, v168, v76
	v_fmac_f32_e32 v193, v169, v77
	v_fmac_f32_e32 v194, v170, v78
	v_fmac_f32_e32 v195, v171, v79
	v_fmac_f32_e32 v188, v164, v72
	v_fmac_f32_e32 v189, v165, v73
	v_cvt_pk_bf16_f32 v164, v192, v193
	v_cvt_pk_bf16_f32 v165, v194, v195
	v_fmac_f32_e32 v190, v166, v74
	v_fmac_f32_e32 v191, v167, v75
	v_cvt_pk_bf16_f32 v166, v188, v189
	v_cvt_pk_bf16_f32 v167, v190, v191
	global_store_dwordx4 v[232:233], v[164:167], off
	v_lshl_add_u64 v[198:199], s[12:13], 0, v[198:199]
	v_lshl_add_u64 v[198:199], v[198:199], 0, v[196:197]
	v_mul_f32_e32 v164, v68, v192
	v_mul_f32_e32 v165, v69, v193
	v_cvt_pk_bf16_f32 v164, v164, v165
	v_mul_f32_e32 v165, v70, v194
	v_mul_f32_e32 v166, v71, v195
	v_cvt_pk_bf16_f32 v165, v165, v166
	v_mul_f32_e32 v166, v60, v188
	v_mul_f32_e32 v167, v61, v189
	v_cvt_pk_bf16_f32 v166, v166, v167
	v_mul_f32_e32 v167, v62, v190
	v_mul_f32_e32 v168, v63, v191
	v_cvt_pk_bf16_f32 v167, v167, v168
	s_and_b64 vcc, exec, s[8:9]
	s_mov_b64 s[22:23], -1
	global_store_dwordx4 v[198:199], v[164:167], off
	s_cbranch_vccnz .LBB0_517
	v_lshlrev_b32_e32 v168, 16, v184
	v_and_b32_e32 v169, 0xffff0000, v184
	v_lshlrev_b32_e32 v170, 16, v185
	v_and_b32_e32 v171, 0xffff0000, v185
	v_lshlrev_b32_e32 v164, 16, v186
	v_and_b32_e32 v165, 0xffff0000, v186
	v_lshlrev_b32_e32 v166, 16, v187
	v_and_b32_e32 v167, 0xffff0000, v187
	s_mov_b64 s[22:23], 0

; __device__ __forceinline__ float bflo(unsigned w) { return __uint_as_float(w << 16); }
; __device__ __forceinline__ float bfhi(unsigned w) { return __uint_as_float(w & 0xffff0000u); }
;   __device__ __forceinline__ void operator()(const f32x4 (&acc)[2][2][4][2], const Unit& u, int wr, int wc, int fr, int fq) const {
;     ...
;         for (int bj = 0; bj < 2; ++bj) {
;           float x[8], rr[8];
;           if (first) {
;             const float* rp = resid_row(*p, true, row) + col0;
;             const float4 r0 = *(const float4*)(rp + bj * PG_HALF), r1 = *(const float4*)(rp + bj * PG_HALF + 4);
;             rr[0] = r0.x; rr[1] = r0.y; rr[2] = r0.z; rr[3] = r0.w; rr[4] = r1.x; rr[5] = r1.y; rr[6] = r1.z; rr[7] = r1.w;
;           } else {
;             const u32x4 rw = rwq[aim][m - mb][bj];
; #pragma unroll
;             for (int q = 0; q < 4; ++q) { rr[q * 2] = bflo(rw[q]); rr[q * 2 + 1] = bfhi(rw[q]); }
;           }
; #pragma unroll
;           for (int n = 0; n < 2; ++n) {
;             const float4 g = gq[bj][n];
;             const f32x4 a = acc[ai][bj][m][n];
;             x[n * 4 + 0] = rr[n * 4 + 0] + g.x * a[0]; x[n * 4 + 1] = rr[n * 4 + 1] + g.y * a[1]; x[n * 4 + 2] = rr[n * 4 + 2] + g.z * a[2]; x[n * 4 + 3] = rr[n * 4 + 3] + g.w * a[3];
;           }
;           { u32x4 xw = {cvtpk(x[0], x[1]), cvtpk(x[2], x[3]), cvtpk(x[4], x[5]), cvtpk(x[6], x[7])}; *(u32x4*)(op + bj * PG_HALF) = xw; }
;           if (emit) {
;             const float4 g0 = gmq[bj][0], g1 = gmq[bj][1];
;             sq += ((x[0] * x[0] + x[1] * x[1]) + (x[2] * x[2] + x[3] * x[3])) + ((x[4] * x[4] + x[5] * x[5]) + (x[6] * x[6] + x[7] * x[7]));
;             u32x4 w = {cvtpk(x[0] * g0.x, x[1] * g0.y), cvtpk(x[2] * g0.z, x[3] * g0.w), cvtpk(x[4] * g1.x, x[5] * g1.y), cvtpk(x[6] * g1.z, x[7] * g1.w)};
;             *(u32x4*)(hp + bj * PG_HALF) = w;
;           }
;         }
;         if (emit) {
;           sq += __int_as_float(__builtin_amdgcn_ds_bpermute((lane ^ 16) << 2, __float_as_int(sq)));
;           sq += __int_as_float(__builtin_amdgcn_ds_bpermute((lane ^ 32) << 2, __float_as_int(sq)));
;           if (fq == 0) ssq[(size_t)row * 16 + u.pn * 4 + wc] = sq;
;         }
.LBB0_519:
	s_cmp_lg_u64 s[82:83], 0
	s_cbranch_scc1 .Lepw_2
	s_waitcnt vmcnt(0)
.Lepw_2:
	v_fmac_f32_e32 v169, v157, v53
	v_fmac_f32_e32 v171, v159, v55
	v_fmac_f32_e32 v166, v154, v50
	v_fmac_f32_e32 v167, v155, v51
	v_cvt_pk_bf16_f32 v155, v166, v167
	v_mul_f32_e32 v184, v193, v193
	v_mul_f32_e32 v185, v195, v195
	v_fmac_f32_e32 v168, v156, v52
	v_fmac_f32_e32 v170, v158, v54
	v_fmac_f32_e32 v164, v152, v48
	v_fmac_f32_e32 v165, v153, v49
	v_cvt_pk_bf16_f32 v152, v168, v169
	v_cvt_pk_bf16_f32 v153, v170, v171
	v_cvt_pk_bf16_f32 v154, v164, v165
	global_store_dwordx4 v[232:233], v[152:155], off offset:256
	v_mul_f32_e32 v156, v171, v171
	v_fmac_f32_e32 v184, v192, v192
	v_mul_f32_e32 v155, v169, v169
	v_fmac_f32_e32 v185, v194, v194
	v_fmac_f32_e32 v155, v168, v168
	v_fmac_f32_e32 v156, v170, v170
	v_add_f32_e32 v184, v184, v185
	v_mul_f32_e32 v185, v189, v189
	v_mul_f32_e32 v186, v191, v191
	v_add_f32_e32 v155, v155, v156
	v_mul_f32_e32 v156, v165, v165
	v_mul_f32_e32 v157, v167, v167
	v_fmac_f32_e32 v185, v188, v188
	v_fmac_f32_e32 v186, v190, v190
	v_fmac_f32_e32 v156, v164, v164
	v_fmac_f32_e32 v157, v166, v166
	v_add_f32_e32 v185, v185, v186
	v_add_f32_e32 v156, v156, v157
	v_add_f32_e32 v184, v184, v185
	v_add_f32_e32 v155, v155, v156
	v_add_f32_e32 v157, v184, v155
	ds_bpermute_b32 v158, v237, v157
	v_mul_f32_e32 v152, v44, v168
	v_mul_f32_e32 v153, v45, v169
	v_cvt_pk_bf16_f32 v154, v152, v153
	v_mul_f32_e32 v152, v46, v170
	v_mul_f32_e32 v153, v47, v171
	v_cvt_pk_bf16_f32 v155, v152, v153
	v_mul_f32_e32 v152, v40, v164
	v_mul_f32_e32 v153, v41, v165
	v_cvt_pk_bf16_f32 v156, v152, v153
	s_waitcnt lgkmcnt(0)
	v_add_f32_e32 v152, v157, v158
	ds_bpermute_b32 v153, v236, v152
	s_lshl_b32 s22, s16, 2
	s_ashr_i32 s23, s22, 31
	v_mul_f32_e32 v157, v42, v166
	v_mul_f32_e32 v158, v43, v167
	v_cvt_pk_bf16_f32 v157, v157, v158
	global_store_dwordx4 v[198:199], v[154:157], off offset:256
	s_and_saveexec_b64 s[0:1], s[4:5]
	s_cbranch_execz .LBB0_521
	v_readlane_b32 s24, v253, 23
	v_lshlrev_b64 v[154:155], 6, v[222:223]
	v_readlane_b32 s25, v253, 24
	s_lshl_b32 s16, s53, 2
	s_waitcnt lgkmcnt(0)
	v_add_f32_e32 v152, v152, v153
	v_lshl_add_u64 v[154:155], s[24:25], 0, v[154:155]
	v_lshl_add_u64 v[154:155], s[22:23], 2, v[154:155]
	v_lshl_add_u64 v[154:155], v[154:155], 0, s[16:17]
	global_store_dword v[154:155], v152, off

; __device__ __forceinline__ float bflo(unsigned w) { return __uint_as_float(w << 16); }
; __device__ __forceinline__ float bfhi(unsigned w) { return __uint_as_float(w & 0xffff0000u); }
;   __device__ __forceinline__ void operator()(const f32x4 (&acc)[2][2][4][2], const Unit& u, int wr, int wc, int fr, int fq) const {
;     ...
;         for (int bj = 0; bj < 2; ++bj) {
;           float x[8], rr[8];
;           if (first) {
;             const float* rp = resid_row(*p, true, row) + col0;
;             const float4 r0 = *(const float4*)(rp + bj * PG_HALF), r1 = *(const float4*)(rp + bj * PG_HALF + 4);
;             rr[0] = r0.x; rr[1] = r0.y; rr[2] = r0.z; rr[3] = r0.w; rr[4] = r1.x; rr[5] = r1.y; rr[6] = r1.z; rr[7] = r1.w;
;           } else {
;             const u32x4 rw = rwq[aim][m - mb][bj];
; #pragma unroll
;             for (int q = 0; q < 4; ++q) { rr[q * 2] = bflo(rw[q]); rr[q * 2 + 1] = bfhi(rw[q]); }
;           }
; #pragma unroll
;           for (int n = 0; n < 2; ++n) {
;             const float4 g = gq[bj][n];
;             const f32x4 a = acc[ai][bj][m][n];
;             x[n * 4 + 0] = rr[n * 4 + 0] + g.x * a[0]; x[n * 4 + 1] = rr[n * 4 + 1] + g.y * a[1]; x[n * 4 + 2] = rr[n * 4 + 2] + g.z * a[2]; x[n * 4 + 3] = rr[n * 4 + 3] + g.w * a[3];
;           }
;           { u32x4 xw = {cvtpk(x[0], x[1]), cvtpk(x[2], x[3]), cvtpk(x[4], x[5]), cvtpk(x[6], x[7])}; *(u32x4*)(op + bj * PG_HALF) = xw; }
.LBB0_525:
	v_lshlrev_b64 v[164:165], 11, v[230:231]
	v_lshl_add_u64 v[166:167], s[86:87], 0, v[164:165]
	v_lshl_add_u64 v[166:167], v[166:167], 0, v[196:197]
	s_cmp_lg_u64 s[82:83], 0
	s_cbranch_scc1 .Lepw_3
	s_waitcnt vmcnt(1)
.Lepw_3:
	v_fmac_f32_e32 v156, v144, v76
	v_fmac_f32_e32 v157, v145, v77
	v_fmac_f32_e32 v158, v146, v78
	v_fmac_f32_e32 v159, v147, v79
	s_cmp_lg_u64 s[82:83], 0
	s_cbranch_scc1 .Lepw_4
	s_waitcnt vmcnt(0)
.Lepw_4:
	v_fmac_f32_e32 v152, v140, v72
	s_waitcnt lgkmcnt(0)
	v_fmac_f32_e32 v153, v141, v73
	v_cvt_pk_bf16_f32 v140, v156, v157
	v_cvt_pk_bf16_f32 v141, v158, v159
	v_fmac_f32_e32 v154, v142, v74
	v_fmac_f32_e32 v155, v143, v75
	v_cvt_pk_bf16_f32 v142, v152, v153
	v_cvt_pk_bf16_f32 v143, v154, v155
	global_store_dwordx4 v[166:167], v[140:143], off
	v_lshl_add_u64 v[164:165], s[12:13], 0, v[164:165]
	v_lshl_add_u64 v[164:165], v[164:165], 0, v[196:197]
	v_mul_f32_e32 v140, v68, v156
	v_mul_f32_e32 v141, v69, v157
	v_cvt_pk_bf16_f32 v140, v140, v141
	v_mul_f32_e32 v141, v70, v158
	v_mul_f32_e32 v142, v71, v159
	v_cvt_pk_bf16_f32 v141, v141, v142
	v_mul_f32_e32 v142, v60, v152
	v_mul_f32_e32 v143, v61, v153
	v_cvt_pk_bf16_f32 v142, v142, v143
	v_mul_f32_e32 v143, v62, v154
	v_mul_f32_e32 v144, v63, v155
	v_cvt_pk_bf16_f32 v143, v143, v144
	s_and_b64 vcc, exec, s[8:9]
	s_mov_b64 s[24:25], -1
	global_store_dwordx4 v[164:165], v[140:143], off
	s_cbranch_vccnz .LBB0_527
	v_lshlrev_b32_e32 v144, 16, v176
	v_and_b32_e32 v145, 0xffff0000, v176
	v_lshlrev_b32_e32 v146, 16, v177
	v_and_b32_e32 v147, 0xffff0000, v177
	v_lshlrev_b32_e32 v140, 16, v178
	v_and_b32_e32 v141, 0xffff0000, v178
	v_lshlrev_b32_e32 v142, 16, v179
	v_and_b32_e32 v143, 0xffff0000, v179
	s_mov_b64 s[24:25], 0

; __device__ __forceinline__ float bflo(unsigned w) { return __uint_as_float(w << 16); }
; __device__ __forceinline__ float bfhi(unsigned w) { return __uint_as_float(w & 0xffff0000u); }
;   __device__ __forceinline__ void operator()(const f32x4 (&acc)[2][2][4][2], const Unit& u, int wr, int wc, int fr, int fq) const {
;     ...
;         for (int bj = 0; bj < 2; ++bj) {
;           float x[8], rr[8];
;           if (first) {
;             const float* rp = resid_row(*p, true, row) + col0;
;             const float4 r0 = *(const float4*)(rp + bj * PG_HALF), r1 = *(const float4*)(rp + bj * PG_HALF + 4);
;             rr[0] = r0.x; rr[1] = r0.y; rr[2] = r0.z; rr[3] = r0.w; rr[4] = r1.x; rr[5] = r1.y; rr[6] = r1.z; rr[7] = r1.w;
;           } else {
;             const u32x4 rw = rwq[aim][m - mb][bj];
; #pragma unroll
;             for (int q = 0; q < 4; ++q) { rr[q * 2] = bflo(rw[q]); rr[q * 2 + 1] = bfhi(rw[q]); }
;           }
; #pragma unroll
;           for (int n = 0; n < 2; ++n) {
;             const float4 g = gq[bj][n];
;             const f32x4 a = acc[ai][bj][m][n];
;             x[n * 4 + 0] = rr[n * 4 + 0] + g.x * a[0]; x[n * 4 + 1] = rr[n * 4 + 1] + g.y * a[1]; x[n * 4 + 2] = rr[n * 4 + 2] + g.z * a[2]; x[n * 4 + 3] = rr[n * 4 + 3] + g.w * a[3];
;           }
;           { u32x4 xw = {cvtpk(x[0], x[1]), cvtpk(x[2], x[3]), cvtpk(x[4], x[5]), cvtpk(x[6], x[7])}; *(u32x4*)(op + bj * PG_HALF) = xw; }
;           if (emit) {
;             const float4 g0 = gmq[bj][0], g1 = gmq[bj][1];
;             sq += ((x[0] * x[0] + x[1] * x[1]) + (x[2] * x[2] + x[3] * x[3])) + ((x[4] * x[4] + x[5] * x[5]) + (x[6] * x[6] + x[7] * x[7]));
;             u32x4 w = {cvtpk(x[0] * g0.x, x[1] * g0.y), cvtpk(x[2] * g0.z, x[3] * g0.w), cvtpk(x[4] * g1.x, x[5] * g1.y), cvtpk(x[6] * g1.z, x[7] * g1.w)};
;             *(u32x4*)(hp + bj * PG_HALF) = w;
;           }
;         }
;         if (emit) {
;           sq += __int_as_float(__builtin_amdgcn_ds_bpermute((lane ^ 16) << 2, __float_as_int(sq)));
;           sq += __int_as_float(__builtin_amdgcn_ds_bpermute((lane ^ 32) << 2, __float_as_int(sq)));
;           if (fq == 0) ssq[(size_t)row * 16 + u.pn * 4 + wc] = sq;
;         }
.LBB0_529:
	s_cmp_lg_u64 s[82:83], 0
	s_cbranch_scc1 .Lepw_5
	s_waitcnt vmcnt(1)
.Lepw_5:
	v_fmac_f32_e32 v145, v133, v53
	v_fmac_f32_e32 v147, v135, v55
	s_cmp_lg_u64 s[82:83], 0
	s_cbranch_scc1 .Lepw_6
	s_waitcnt vmcnt(0)
.Lepw_6:
	v_fmac_f32_e32 v142, v130, v50
	v_fmac_f32_e32 v143, v131, v51
	v_cvt_pk_bf16_f32 v131, v142, v143
	v_fmac_f32_e32 v144, v132, v52
	v_fmac_f32_e32 v146, v134, v54
	v_fmac_f32_e32 v140, v128, v48
	v_fmac_f32_e32 v141, v129, v49
	v_cvt_pk_bf16_f32 v128, v144, v145
	v_cvt_pk_bf16_f32 v129, v146, v147
	v_cvt_pk_bf16_f32 v130, v140, v141
	global_store_dwordx4 v[166:167], v[128:131], off offset:256
	v_mul_f32_e32 v132, v147, v147
	v_mul_f32_e32 v157, v157, v157
	v_mul_f32_e32 v131, v145, v145
	v_mul_f32_e32 v153, v153, v153
	v_fmac_f32_e32 v131, v144, v144
	v_fmac_f32_e32 v132, v146, v146
	v_fmac_f32_e32 v157, v156, v156
	v_mul_f32_e32 v156, v159, v159
	v_fmac_f32_e32 v153, v152, v152
	v_mul_f32_e32 v152, v155, v155
	v_add_f32_e32 v131, v131, v132
	v_mul_f32_e32 v132, v141, v141
	v_mul_f32_e32 v133, v143, v143
	v_fmac_f32_e32 v156, v158, v158
	v_fmac_f32_e32 v152, v154, v154
	v_fmac_f32_e32 v132, v140, v140
	v_fmac_f32_e32 v133, v142, v142
	v_add_f32_e32 v156, v157, v156
	v_add_f32_e32 v152, v153, v152
	v_add_f32_e32 v132, v132, v133
	v_add_f32_e32 v152, v156, v152
	v_add_f32_e32 v131, v131, v132
	v_add_f32_e32 v133, v152, v131
	ds_bpermute_b32 v134, v237, v133
	v_mul_f32_e32 v128, v44, v144
	v_mul_f32_e32 v129, v45, v145
	v_cvt_pk_bf16_f32 v130, v128, v129
	v_mul_f32_e32 v128, v46, v146
	v_mul_f32_e32 v129, v47, v147
	v_cvt_pk_bf16_f32 v131, v128, v129
	v_mul_f32_e32 v128, v40, v140
	v_mul_f32_e32 v129, v41, v141
	v_cvt_pk_bf16_f32 v132, v128, v129
	s_waitcnt lgkmcnt(0)
	v_add_f32_e32 v128, v133, v134
	ds_bpermute_b32 v129, v236, v128
	v_mul_f32_e32 v133, v42, v142
	v_mul_f32_e32 v134, v43, v143
	v_cvt_pk_bf16_f32 v133, v133, v134
	global_store_dwordx4 v[164:165], v[130:133], off offset:256
	s_and_saveexec_b64 s[0:1], s[4:5]
	s_cbranch_execz .LBB0_531
	v_readlane_b32 s24, v253, 23
	v_lshlrev_b64 v[130:131], 6, v[230:231]
	v_readlane_b32 s25, v253, 24
	s_lshl_b32 s16, s53, 2
	s_waitcnt lgkmcnt(0)
	v_add_f32_e32 v128, v128, v129
	v_lshl_add_u64 v[130:131], s[24:25], 0, v[130:131]
	v_lshl_add_u64 v[130:131], s[22:23], 2, v[130:131]
	v_lshl_add_u64 v[130:131], v[130:131], 0, s[16:17]
	global_store_dword v[130:131], v128, off

; __device__ __forceinline__ float bflo(unsigned w) { return __uint_as_float(w << 16); }
; __device__ __forceinline__ float bfhi(unsigned w) { return __uint_as_float(w & 0xffff0000u); }
;   __device__ __forceinline__ void operator()(const f32x4 (&acc)[2][2][4][2], const Unit& u, int wr, int wc, int fr, int fq) const {
;     ...
;         for (int bj = 0; bj < 2; ++bj) {
;           float x[8], rr[8];
;           if (first) {
;             const float* rp = resid_row(*p, true, row) + col0;
;             const float4 r0 = *(const float4*)(rp + bj * PG_HALF), r1 = *(const float4*)(rp + bj * PG_HALF + 4);
;             rr[0] = r0.x; rr[1] = r0.y; rr[2] = r0.z; rr[3] = r0.w; rr[4] = r1.x; rr[5] = r1.y; rr[6] = r1.z; rr[7] = r1.w;
;           } else {
;             const u32x4 rw = rwq[aim][m - mb][bj];
; #pragma unroll
;             for (int q = 0; q < 4; ++q) { rr[q * 2] = bflo(rw[q]); rr[q * 2 + 1] = bfhi(rw[q]); }
;           }
; #pragma unroll
;           for (int n = 0; n < 2; ++n) {
;             const float4 g = gq[bj][n];
;             const f32x4 a = acc[ai][bj][m][n];
;             x[n * 4 + 0] = rr[n * 4 + 0] + g.x * a[0]; x[n * 4 + 1] = rr[n * 4 + 1] + g.y * a[1]; x[n * 4 + 2] = rr[n * 4 + 2] + g.z * a[2]; x[n * 4 + 3] = rr[n * 4 + 3] + g.w * a[3];
;           }
;           { u32x4 xw = {cvtpk(x[0], x[1]), cvtpk(x[2], x[3]), cvtpk(x[4], x[5]), cvtpk(x[6], x[7])}; *(u32x4*)(op + bj * PG_HALF) = xw; }
.LBB0_537:
	v_lshlrev_b64 v[164:165], 11, v[228:229]
	v_lshl_add_u64 v[166:167], s[86:87], 0, v[164:165]
	v_lshl_add_u64 v[166:167], v[166:167], 0, v[196:197]
	s_cmp_lg_u64 s[82:83], 0
	s_cbranch_scc1 .Lepw_7
	s_waitcnt vmcnt(1)
.Lepw_7:
	v_fmac_f32_e32 v156, v124, v76
	v_fmac_f32_e32 v157, v125, v77
	v_fmac_f32_e32 v158, v126, v78
	v_fmac_f32_e32 v159, v127, v79
	s_cmp_lg_u64 s[82:83], 0
	s_cbranch_scc1 .Lepw_8
	s_waitcnt vmcnt(0)
.Lepw_8:
	v_fmac_f32_e32 v152, v120, v72
	v_fmac_f32_e32 v153, v121, v73
	v_cvt_pk_bf16_f32 v120, v156, v157
	v_cvt_pk_bf16_f32 v121, v158, v159
	v_fmac_f32_e32 v154, v122, v74
	v_fmac_f32_e32 v155, v123, v75
	v_cvt_pk_bf16_f32 v122, v152, v153
	v_cvt_pk_bf16_f32 v123, v154, v155
	global_store_dwordx4 v[166:167], v[120:123], off
	v_lshl_add_u64 v[164:165], s[12:13], 0, v[164:165]
	v_lshl_add_u64 v[164:165], v[164:165], 0, v[196:197]
	v_mul_f32_e32 v120, v68, v156
	v_mul_f32_e32 v121, v69, v157
	v_cvt_pk_bf16_f32 v120, v120, v121
	v_mul_f32_e32 v121, v70, v158
	v_mul_f32_e32 v122, v71, v159
	v_cvt_pk_bf16_f32 v121, v121, v122
	v_mul_f32_e32 v122, v60, v152
	v_mul_f32_e32 v123, v61, v153
	v_cvt_pk_bf16_f32 v122, v122, v123
	v_mul_f32_e32 v123, v62, v154
	v_mul_f32_e32 v124, v63, v155
	v_cvt_pk_bf16_f32 v123, v123, v124
	s_and_b64 vcc, exec, s[8:9]
	s_mov_b64 s[24:25], -1
	global_store_dwordx4 v[164:165], v[120:123], off
	s_cbranch_vccnz .LBB0_539
	v_lshlrev_b32_e32 v124, 16, v160
	v_and_b32_e32 v125, 0xffff0000, v160
	v_lshlrev_b32_e32 v126, 16, v161
	v_and_b32_e32 v127, 0xffff0000, v161
	v_lshlrev_b32_e32 v120, 16, v162
	v_and_b32_e32 v121, 0xffff0000, v162
	v_lshlrev_b32_e32 v122, 16, v163
	v_and_b32_e32 v123, 0xffff0000, v163
	s_mov_b64 s[24:25], 0

; __device__ __forceinline__ float bflo(unsigned w) { return __uint_as_float(w << 16); }
; __device__ __forceinline__ float bfhi(unsigned w) { return __uint_as_float(w & 0xffff0000u); }
;   __device__ __forceinline__ void operator()(const f32x4 (&acc)[2][2][4][2], const Unit& u, int wr, int wc, int fr, int fq) const {
;     ...
;         for (int bj = 0; bj < 2; ++bj) {
;           float x[8], rr[8];
;           if (first) {
;             const float* rp = resid_row(*p, true, row) + col0;
;             const float4 r0 = *(const float4*)(rp + bj * PG_HALF), r1 = *(const float4*)(rp + bj * PG_HALF + 4);
;             rr[0] = r0.x; rr[1] = r0.y; rr[2] = r0.z; rr[3] = r0.w; rr[4] = r1.x; rr[5] = r1.y; rr[6] = r1.z; rr[7] = r1.w;
;           } else {
;             const u32x4 rw = rwq[aim][m - mb][bj];
; #pragma unroll
;             for (int q = 0; q < 4; ++q) { rr[q * 2] = bflo(rw[q]); rr[q * 2 + 1] = bfhi(rw[q]); }
;           }
; #pragma unroll
;           for (int n = 0; n < 2; ++n) {
;             const float4 g = gq[bj][n];
;             const f32x4 a = acc[ai][bj][m][n];
;             x[n * 4 + 0] = rr[n * 4 + 0] + g.x * a[0]; x[n * 4 + 1] = rr[n * 4 + 1] + g.y * a[1]; x[n * 4 + 2] = rr[n * 4 + 2] + g.z * a[2]; x[n * 4 + 3] = rr[n * 4 + 3] + g.w * a[3];
;           }
;           { u32x4 xw = {cvtpk(x[0], x[1]), cvtpk(x[2], x[3]), cvtpk(x[4], x[5]), cvtpk(x[6], x[7])}; *(u32x4*)(op + bj * PG_HALF) = xw; }
;           if (emit) {
;             const float4 g0 = gmq[bj][0], g1 = gmq[bj][1];
;             sq += ((x[0] * x[0] + x[1] * x[1]) + (x[2] * x[2] + x[3] * x[3])) + ((x[4] * x[4] + x[5] * x[5]) + (x[6] * x[6] + x[7] * x[7]));
;             u32x4 w = {cvtpk(x[0] * g0.x, x[1] * g0.y), cvtpk(x[2] * g0.z, x[3] * g0.w), cvtpk(x[4] * g1.x, x[5] * g1.y), cvtpk(x[6] * g1.z, x[7] * g1.w)};
;             *(u32x4*)(hp + bj * PG_HALF) = w;
;           }
;         }
;         if (emit) {
;           sq += __int_as_float(__builtin_amdgcn_ds_bpermute((lane ^ 16) << 2, __float_as_int(sq)));
;           sq += __int_as_float(__builtin_amdgcn_ds_bpermute((lane ^ 32) << 2, __float_as_int(sq)));
;           if (fq == 0) ssq[(size_t)row * 16 + u.pn * 4 + wc] = sq;
;         }
.Lepw_9:
	v_fmac_f32_e32 v125, v117, v53
	v_fmac_f32_e32 v127, v119, v55
	s_cmp_lg_u64 s[82:83], 0
	s_cbranch_scc1 .Lepw_10
	s_waitcnt vmcnt(0)
.Lepw_10:
	v_fmac_f32_e32 v122, v114, v50
	v_fmac_f32_e32 v123, v115, v51
	v_cvt_pk_bf16_f32 v115, v122, v123
	v_fmac_f32_e32 v124, v116, v52
	v_fmac_f32_e32 v126, v118, v54
	v_fmac_f32_e32 v120, v112, v48
	v_fmac_f32_e32 v121, v113, v49
	v_cvt_pk_bf16_f32 v112, v124, v125
	v_cvt_pk_bf16_f32 v113, v126, v127
	v_cvt_pk_bf16_f32 v114, v120, v121
	global_store_dwordx4 v[166:167], v[112:115], off offset:256
	v_mul_f32_e32 v116, v127, v127
	v_mul_f32_e32 v157, v157, v157
	v_mul_f32_e32 v115, v125, v125
	v_mul_f32_e32 v153, v153, v153
	v_fmac_f32_e32 v115, v124, v124
	v_fmac_f32_e32 v116, v126, v126
	v_fmac_f32_e32 v157, v156, v156
	v_mul_f32_e32 v156, v159, v159
	v_fmac_f32_e32 v153, v152, v152
	v_mul_f32_e32 v152, v155, v155
	v_add_f32_e32 v115, v115, v116
	v_mul_f32_e32 v116, v121, v121
	v_mul_f32_e32 v117, v123, v123
	v_fmac_f32_e32 v156, v158, v158
	v_fmac_f32_e32 v152, v154, v154
	v_fmac_f32_e32 v116, v120, v120
	v_fmac_f32_e32 v117, v122, v122
	v_add_f32_e32 v156, v157, v156
	v_add_f32_e32 v152, v153, v152
	v_add_f32_e32 v116, v116, v117
	v_add_f32_e32 v152, v156, v152
	v_add_f32_e32 v115, v115, v116
	v_add_f32_e32 v117, v152, v115
	ds_bpermute_b32 v118, v237, v117
	v_mul_f32_e32 v112, v44, v124
	v_mul_f32_e32 v113, v45, v125
	v_cvt_pk_bf16_f32 v114, v112, v113
	v_mul_f32_e32 v112, v46, v126
	v_mul_f32_e32 v113, v47, v127
	v_cvt_pk_bf16_f32 v115, v112, v113
	v_mul_f32_e32 v112, v40, v120
	v_mul_f32_e32 v113, v41, v121
	v_cvt_pk_bf16_f32 v116, v112, v113
	s_waitcnt lgkmcnt(0)
	v_add_f32_e32 v112, v117, v118
	ds_bpermute_b32 v113, v236, v112
	v_mul_f32_e32 v117, v42, v122
	v_mul_f32_e32 v118, v43, v123
	v_cvt_pk_bf16_f32 v117, v117, v118
	global_store_dwordx4 v[164:165], v[114:117], off offset:256
	s_and_saveexec_b64 s[0:1], s[4:5]
	s_cbranch_execz .LBB0_543
	v_readlane_b32 s24, v253, 23
	v_lshlrev_b64 v[114:115], 6, v[228:229]
	v_readlane_b32 s25, v253, 24
	s_lshl_b32 s16, s53, 2
	s_waitcnt lgkmcnt(0)
	v_add_f32_e32 v112, v112, v113
	v_lshl_add_u64 v[114:115], s[24:25], 0, v[114:115]
	v_lshl_add_u64 v[114:115], s[22:23], 2, v[114:115]
	v_lshl_add_u64 v[114:115], v[114:115], 0, s[16:17]
	global_store_dword v[114:115], v112, off

; __device__ __forceinline__ float bflo(unsigned w) { return __uint_as_float(w << 16); }
; __device__ __forceinline__ float bfhi(unsigned w) { return __uint_as_float(w & 0xffff0000u); }
;   __device__ __forceinline__ void operator()(const f32x4 (&acc)[2][2][4][2], const Unit& u, int wr, int wc, int fr, int fq) const {
;     ...
;         for (int bj = 0; bj < 2; ++bj) {
;           float x[8], rr[8];
;           if (first) {
;             const float* rp = resid_row(*p, true, row) + col0;
;             const float4 r0 = *(const float4*)(rp + bj * PG_HALF), r1 = *(const float4*)(rp + bj * PG_HALF + 4);
;             rr[0] = r0.x; rr[1] = r0.y; rr[2] = r0.z; rr[3] = r0.w; rr[4] = r1.x; rr[5] = r1.y; rr[6] = r1.z; rr[7] = r1.w;
;           } else {
;             const u32x4 rw = rwq[aim][m - mb][bj];
; #pragma unroll
;             for (int q = 0; q < 4; ++q) { rr[q * 2] = bflo(rw[q]); rr[q * 2 + 1] = bfhi(rw[q]); }
;           }
; #pragma unroll
;           for (int n = 0; n < 2; ++n) {
;             const float4 g = gq[bj][n];
;             const f32x4 a = acc[ai][bj][m][n];
;             x[n * 4 + 0] = rr[n * 4 + 0] + g.x * a[0]; x[n * 4 + 1] = rr[n * 4 + 1] + g.y * a[1]; x[n * 4 + 2] = rr[n * 4 + 2] + g.z * a[2]; x[n * 4 + 3] = rr[n * 4 + 3] + g.w * a[3];
;           }
;           { u32x4 xw = {cvtpk(x[0], x[1]), cvtpk(x[2], x[3]), cvtpk(x[4], x[5]), cvtpk(x[6], x[7])}; *(u32x4*)(op + bj * PG_HALF) = xw; }
.LBB0_547:
	v_lshlrev_b64 v[120:121], 11, v[226:227]
	v_lshl_add_u64 v[122:123], s[86:87], 0, v[120:121]
	v_lshl_add_u64 v[122:123], v[122:123], 0, v[196:197]
	s_cmp_lg_u64 s[82:83], 0
	s_cbranch_scc1 .Lepw_11
	s_waitcnt vmcnt(1)
.Lepw_11:
	v_fmac_f32_e32 v116, v108, v76
	v_fmac_f32_e32 v117, v109, v77
	v_fmac_f32_e32 v118, v110, v78
	v_fmac_f32_e32 v119, v111, v79
	s_cmp_lg_u64 s[82:83], 0
	s_cbranch_scc1 .Lepw_12
	s_waitcnt vmcnt(0)
.Lepw_12:
	v_fmac_f32_e32 v112, v104, v72
	s_waitcnt lgkmcnt(0)
	v_fmac_f32_e32 v113, v105, v73
	v_cvt_pk_bf16_f32 v104, v116, v117
	v_cvt_pk_bf16_f32 v105, v118, v119
	v_fmac_f32_e32 v114, v106, v74
	v_fmac_f32_e32 v115, v107, v75
	v_cvt_pk_bf16_f32 v106, v112, v113
	v_cvt_pk_bf16_f32 v107, v114, v115
	global_store_dwordx4 v[122:123], v[104:107], off
	v_lshl_add_u64 v[120:121], s[12:13], 0, v[120:121]
	v_lshl_add_u64 v[120:121], v[120:121], 0, v[196:197]
	v_mul_f32_e32 v104, v68, v116
	v_mul_f32_e32 v105, v69, v117
	v_cvt_pk_bf16_f32 v104, v104, v105
	v_mul_f32_e32 v105, v70, v118
	v_mul_f32_e32 v106, v71, v119
	v_cvt_pk_bf16_f32 v105, v105, v106
	v_mul_f32_e32 v106, v60, v112
	v_mul_f32_e32 v107, v61, v113
	v_cvt_pk_bf16_f32 v106, v106, v107
	v_mul_f32_e32 v107, v62, v114
	v_mul_f32_e32 v108, v63, v115
	v_cvt_pk_bf16_f32 v107, v107, v108
	s_and_b64 vcc, exec, s[8:9]
	s_mov_b64 s[24:25], -1
	global_store_dwordx4 v[120:121], v[104:107], off
	s_cbranch_vccnz .LBB0_549
	v_lshlrev_b32_e32 v108, 16, v136
	v_and_b32_e32 v109, 0xffff0000, v136
	v_lshlrev_b32_e32 v110, 16, v137
	v_and_b32_e32 v111, 0xffff0000, v137
	v_lshlrev_b32_e32 v104, 16, v138
	v_and_b32_e32 v105, 0xffff0000, v138
	v_lshlrev_b32_e32 v106, 16, v139
	v_and_b32_e32 v107, 0xffff0000, v139
	s_mov_b64 s[24:25], 0

; __device__ __forceinline__ float bflo(unsigned w) { return __uint_as_float(w << 16); }
; __device__ __forceinline__ float bfhi(unsigned w) { return __uint_as_float(w & 0xffff0000u); }
;   __device__ __forceinline__ void operator()(const f32x4 (&acc)[2][2][4][2], const Unit& u, int wr, int wc, int fr, int fq) const {
;     ...
;         for (int bj = 0; bj < 2; ++bj) {
;           float x[8], rr[8];
;           if (first) {
;             const float* rp = resid_row(*p, true, row) + col0;
;             const float4 r0 = *(const float4*)(rp + bj * PG_HALF), r1 = *(const float4*)(rp + bj * PG_HALF + 4);
;             rr[0] = r0.x; rr[1] = r0.y; rr[2] = r0.z; rr[3] = r0.w; rr[4] = r1.x; rr[5] = r1.y; rr[6] = r1.z; rr[7] = r1.w;
;           } else {
;             const u32x4 rw = rwq[aim][m - mb][bj];
; #pragma unroll
;             for (int q = 0; q < 4; ++q) { rr[q * 2] = bflo(rw[q]); rr[q * 2 + 1] = bfhi(rw[q]); }
;           }
; #pragma unroll
;           for (int n = 0; n < 2; ++n) {
;             const float4 g = gq[bj][n];
;             const f32x4 a = acc[ai][bj][m][n];
;             x[n * 4 + 0] = rr[n * 4 + 0] + g.x * a[0]; x[n * 4 + 1] = rr[n * 4 + 1] + g.y * a[1]; x[n * 4 + 2] = rr[n * 4 + 2] + g.z * a[2]; x[n * 4 + 3] = rr[n * 4 + 3] + g.w * a[3];
;           }
;           { u32x4 xw = {cvtpk(x[0], x[1]), cvtpk(x[2], x[3]), cvtpk(x[4], x[5]), cvtpk(x[6], x[7])}; *(u32x4*)(op + bj * PG_HALF) = xw; }
;           if (emit) {
;             const float4 g0 = gmq[bj][0], g1 = gmq[bj][1];
;             sq += ((x[0] * x[0] + x[1] * x[1]) + (x[2] * x[2] + x[3] * x[3])) + ((x[4] * x[4] + x[5] * x[5]) + (x[6] * x[6] + x[7] * x[7]));
;             u32x4 w = {cvtpk(x[0] * g0.x, x[1] * g0.y), cvtpk(x[2] * g0.z, x[3] * g0.w), cvtpk(x[4] * g1.x, x[5] * g1.y), cvtpk(x[6] * g1.z, x[7] * g1.w)};
;             *(u32x4*)(hp + bj * PG_HALF) = w;
;           }
;         }
;         if (emit) {
;           sq += __int_as_float(__builtin_amdgcn_ds_bpermute((lane ^ 16) << 2, __float_as_int(sq)));
;           sq += __int_as_float(__builtin_amdgcn_ds_bpermute((lane ^ 32) << 2, __float_as_int(sq)));
;           if (fq == 0) ssq[(size_t)row * 16 + u.pn * 4 + wc] = sq;
;         }
.Lepw_13:
	v_fmac_f32_e32 v109, v101, v53
	v_fmac_f32_e32 v111, v103, v55
	s_cmp_lg_u64 s[82:83], 0
	s_cbranch_scc1 .Lepw_14
	s_waitcnt vmcnt(0)
.Lepw_14:
	v_fmac_f32_e32 v106, v98, v50
	v_fmac_f32_e32 v107, v99, v51
	v_cvt_pk_bf16_f32 v99, v106, v107
	v_fmac_f32_e32 v108, v100, v52
	v_fmac_f32_e32 v110, v102, v54
	v_fmac_f32_e32 v104, v96, v48
	v_fmac_f32_e32 v105, v97, v49
	v_cvt_pk_bf16_f32 v96, v108, v109
	v_cvt_pk_bf16_f32 v97, v110, v111
	v_cvt_pk_bf16_f32 v98, v104, v105
	global_store_dwordx4 v[122:123], v[96:99], off offset:256
	v_mul_f32_e32 v100, v111, v111
	v_mul_f32_e32 v117, v117, v117
	v_mul_f32_e32 v99, v109, v109
	v_mul_f32_e32 v113, v113, v113
	v_fmac_f32_e32 v99, v108, v108
	v_fmac_f32_e32 v100, v110, v110
	v_fmac_f32_e32 v117, v116, v116
	v_mul_f32_e32 v116, v119, v119
	v_fmac_f32_e32 v113, v112, v112
	v_mul_f32_e32 v112, v115, v115
	v_add_f32_e32 v99, v99, v100
	v_mul_f32_e32 v100, v105, v105
	v_mul_f32_e32 v101, v107, v107
	v_fmac_f32_e32 v116, v118, v118
	v_fmac_f32_e32 v112, v114, v114
	v_fmac_f32_e32 v100, v104, v104
	v_fmac_f32_e32 v101, v106, v106
	v_add_f32_e32 v116, v117, v116
	v_add_f32_e32 v112, v113, v112
	v_add_f32_e32 v100, v100, v101
	v_add_f32_e32 v112, v116, v112
	v_add_f32_e32 v99, v99, v100
	v_add_f32_e32 v101, v112, v99
	ds_bpermute_b32 v102, v237, v101
	v_mul_f32_e32 v96, v44, v108
	v_mul_f32_e32 v97, v45, v109
	v_cvt_pk_bf16_f32 v98, v96, v97
	v_mul_f32_e32 v96, v46, v110
	v_mul_f32_e32 v97, v47, v111
	v_cvt_pk_bf16_f32 v99, v96, v97
	v_mul_f32_e32 v96, v40, v104
	v_mul_f32_e32 v97, v41, v105
	v_cvt_pk_bf16_f32 v100, v96, v97
	s_waitcnt lgkmcnt(0)
	v_add_f32_e32 v96, v101, v102
	ds_bpermute_b32 v97, v236, v96
	v_mul_f32_e32 v101, v42, v106
	v_mul_f32_e32 v102, v43, v107
	v_cvt_pk_bf16_f32 v101, v101, v102
	global_store_dwordx4 v[120:121], v[98:101], off offset:256
	s_and_saveexec_b64 s[0:1], s[4:5]
	s_cbranch_execz .LBB0_553
	v_readlane_b32 s24, v253, 23
	v_lshlrev_b64 v[98:99], 6, v[226:227]
	v_readlane_b32 s25, v253, 24
	s_lshl_b32 s16, s53, 2
	s_waitcnt lgkmcnt(0)
	v_add_f32_e32 v96, v96, v97
	v_lshl_add_u64 v[98:99], s[24:25], 0, v[98:99]
	v_lshl_add_u64 v[98:99], s[22:23], 2, v[98:99]
	v_lshl_add_u64 v[98:99], v[98:99], 0, s[16:17]
	global_store_dword v[98:99], v96, off

; __device__ __forceinline__ float bflo(unsigned w) { return __uint_as_float(w << 16); }
; __device__ __forceinline__ float bfhi(unsigned w) { return __uint_as_float(w & 0xffff0000u); }
;   __device__ __forceinline__ void operator()(const f32x4 (&acc)[2][2][4][2], const Unit& u, int wr, int wc, int fr, int fq) const {
;     ...
;     for (int aim = 0; aim < 4; ++aim) {
;       const int ai = aim >> 1, mb = (aim & 1) * 2;
;       if (!first && aim < 3) {
;         const int ai2 = (aim + 1) >> 1, mb2 = ((aim + 1) & 1) * 2;
; #pragma unroll
;         for (int m = 0; m < 2; ++m) {
;           const u16* op = (const u16*)(p->ws + OFF_XS) + (size_t)(row0 + ai2 * PG_HALF + (mb2 + m) * 16) * 1024 + col0;
; #pragma unroll
;           for (int bj = 0; bj < 2; ++bj) rwq[aim + 1][m][bj] = *(const u32x4*)(op + bj * PG_HALF);
;         }
;       }
;     ...
;             const u32x4 rw = rwq[aim][m - mb][bj];
; #pragma unroll
;             for (int q = 0; q < 4; ++q) { rr[q * 2] = bflo(rw[q]); rr[q * 2 + 1] = bfhi(rw[q]); }
.LBB0_555:
	s_movk_i32 s0, 0x7f80
	v_cmp_gt_i32_e64 s[0:1], s0, v222
	s_and_b64 vcc, exec, s[8:9]
	s_mov_b64 s[24:25], -1
	s_cbranch_vccnz .LBB0_557
	s_waitcnt vmcnt(4)
	v_lshlrev_b32_e32 v116, 16, v144
	v_and_b32_e32 v117, 0xffff0000, v144
	v_lshlrev_b32_e32 v118, 16, v145
	v_and_b32_e32 v119, 0xffff0000, v145
	v_lshlrev_b32_e32 v112, 16, v146
	v_and_b32_e32 v113, 0xffff0000, v146
	v_lshlrev_b32_e32 v114, 16, v147
	v_and_b32_e32 v115, 0xffff0000, v147
	s_mov_b64 s[24:25], 0

; __device__ __forceinline__ float bflo(unsigned w) { return __uint_as_float(w << 16); }
; __device__ __forceinline__ float bfhi(unsigned w) { return __uint_as_float(w & 0xffff0000u); }
;   __device__ __forceinline__ void operator()(const f32x4 (&acc)[2][2][4][2], const Unit& u, int wr, int wc, int fr, int fq) const {
;     ...
;         for (int bj = 0; bj < 2; ++bj) {
;           float x[8], rr[8];
;           if (first) {
;             const float* rp = resid_row(*p, true, row) + col0;
;             const float4 r0 = *(const float4*)(rp + bj * PG_HALF), r1 = *(const float4*)(rp + bj * PG_HALF + 4);
;             rr[0] = r0.x; rr[1] = r0.y; rr[2] = r0.z; rr[3] = r0.w; rr[4] = r1.x; rr[5] = r1.y; rr[6] = r1.z; rr[7] = r1.w;
;           } else {
;             const u32x4 rw = rwq[aim][m - mb][bj];
; #pragma unroll
;             for (int q = 0; q < 4; ++q) { rr[q * 2] = bflo(rw[q]); rr[q * 2 + 1] = bfhi(rw[q]); }
;           }
; #pragma unroll
;           for (int n = 0; n < 2; ++n) {
;             const float4 g = gq[bj][n];
;             const f32x4 a = acc[ai][bj][m][n];
;             x[n * 4 + 0] = rr[n * 4 + 0] + g.x * a[0]; x[n * 4 + 1] = rr[n * 4 + 1] + g.y * a[1]; x[n * 4 + 2] = rr[n * 4 + 2] + g.z * a[2]; x[n * 4 + 3] = rr[n * 4 + 3] + g.w * a[3];
;           }
;           { u32x4 xw = {cvtpk(x[0], x[1]), cvtpk(x[2], x[3]), cvtpk(x[4], x[5]), cvtpk(x[6], x[7])}; *(u32x4*)(op + bj * PG_HALF) = xw; }
.LBB0_559:
	v_lshlrev_b64 v[122:123], 11, v[120:121]
	v_lshl_add_u64 v[124:125], s[86:87], 0, v[122:123]
	v_lshl_add_u64 v[124:125], v[124:125], 0, v[196:197]
	s_cmp_lg_u64 s[82:83], 0
	s_cbranch_scc1 .Lepw_15
	s_waitcnt vmcnt(1)
.Lepw_15:
	v_fmac_f32_e32 v116, v92, v76
	v_fmac_f32_e32 v117, v93, v77
	v_fmac_f32_e32 v118, v94, v78
	v_fmac_f32_e32 v119, v95, v79
	s_cmp_lg_u64 s[82:83], 0
	s_cbranch_scc1 .Lepw_16
	s_waitcnt vmcnt(0)
.Lepw_16:
	v_fmac_f32_e32 v112, v88, v72
	v_fmac_f32_e32 v113, v89, v73
	v_cvt_pk_bf16_f32 v88, v116, v117
	v_cvt_pk_bf16_f32 v89, v118, v119
	v_fmac_f32_e32 v114, v90, v74
	v_fmac_f32_e32 v115, v91, v75
	v_cvt_pk_bf16_f32 v90, v112, v113
	v_cvt_pk_bf16_f32 v91, v114, v115
	global_store_dwordx4 v[124:125], v[88:91], off
	v_lshl_add_u64 v[122:123], s[12:13], 0, v[122:123]
	v_lshl_add_u64 v[122:123], v[122:123], 0, v[196:197]
	v_mul_f32_e32 v88, v68, v116
	v_mul_f32_e32 v89, v69, v117
	v_cvt_pk_bf16_f32 v88, v88, v89
	v_mul_f32_e32 v89, v70, v118
	v_mul_f32_e32 v90, v71, v119
	v_cvt_pk_bf16_f32 v89, v89, v90
	v_mul_f32_e32 v90, v60, v112
	v_mul_f32_e32 v91, v61, v113
	v_cvt_pk_bf16_f32 v90, v90, v91
	v_mul_f32_e32 v91, v62, v114
	v_mul_f32_e32 v92, v63, v115
	v_cvt_pk_bf16_f32 v91, v91, v92
	s_and_b64 vcc, exec, s[8:9]
	s_mov_b64 s[24:25], -1
	global_store_dwordx4 v[122:123], v[88:91], off
	s_cbranch_vccnz .LBB0_561
	v_lshlrev_b32_e32 v92, 16, v140
	v_and_b32_e32 v93, 0xffff0000, v140
	v_lshlrev_b32_e32 v94, 16, v141
	v_and_b32_e32 v95, 0xffff0000, v141
	v_lshlrev_b32_e32 v88, 16, v142
	v_and_b32_e32 v89, 0xffff0000, v142
	v_lshlrev_b32_e32 v90, 16, v143
	v_and_b32_e32 v91, 0xffff0000, v143
	s_mov_b64 s[24:25], 0

;   __device__ __forceinline__ void operator()(const f32x4 (&acc)[2][2][4][2], const Unit& u, int wr, int wc, int fr, int fq) const {
;     ...
; #pragma unroll
;           for (int n = 0; n < 2; ++n) {
;             const float4 g = gq[bj][n];
;             const f32x4 a = acc[ai][bj][m][n];
;             x[n * 4 + 0] = rr[n * 4 + 0] + g.x * a[0]; x[n * 4 + 1] = rr[n * 4 + 1] + g.y * a[1]; x[n * 4 + 2] = rr[n * 4 + 2] + g.z * a[2]; x[n * 4 + 3] = rr[n * 4 + 3] + g.w * a[3];
;           }
;           { u32x4 xw = {cvtpk(x[0], x[1]), cvtpk(x[2], x[3]), cvtpk(x[4], x[5]), cvtpk(x[6], x[7])}; *(u32x4*)(op + bj * PG_HALF) = xw; }
;           if (emit) {
;             const float4 g0 = gmq[bj][0], g1 = gmq[bj][1];
;             sq += ((x[0] * x[0] + x[1] * x[1]) + (x[2] * x[2] + x[3] * x[3])) + ((x[4] * x[4] + x[5] * x[5]) + (x[6] * x[6] + x[7] * x[7]));
;             u32x4 w = {cvtpk(x[0] * g0.x, x[1] * g0.y), cvtpk(x[2] * g0.z, x[3] * g0.w), cvtpk(x[4] * g1.x, x[5] * g1.y), cvtpk(x[6] * g1.z, x[7] * g1.w)};
;             *(u32x4*)(hp + bj * PG_HALF) = w;
;           }
;         }
;         if (emit) {
;           sq += __int_as_float(__builtin_amdgcn_ds_bpermute((lane ^ 16) << 2, __float_as_int(sq)));
;           sq += __int_as_float(__builtin_amdgcn_ds_bpermute((lane ^ 32) << 2, __float_as_int(sq)));
;           if (fq == 0) ssq[(size_t)row * 16 + u.pn * 4 + wc] = sq;
.Lepw_17:
	v_fmac_f32_e32 v93, v85, v53
	v_fmac_f32_e32 v95, v87, v55
	s_cmp_lg_u64 s[82:83], 0
	s_cbranch_scc1 .Lepw_18
	s_waitcnt vmcnt(0)
.Lepw_18:
	v_fmac_f32_e32 v90, v82, v50
	v_fmac_f32_e32 v91, v83, v51
	v_cvt_pk_bf16_f32 v83, v90, v91
	v_fmac_f32_e32 v92, v84, v52
	v_fmac_f32_e32 v94, v86, v54
	v_fmac_f32_e32 v88, v80, v48
	v_fmac_f32_e32 v89, v81, v49
	v_cvt_pk_bf16_f32 v80, v92, v93
	v_cvt_pk_bf16_f32 v81, v94, v95
	v_cvt_pk_bf16_f32 v82, v88, v89
	global_store_dwordx4 v[124:125], v[80:83], off offset:256
	v_mul_f32_e32 v84, v95, v95
	v_mul_f32_e32 v117, v117, v117
	v_mul_f32_e32 v83, v93, v93
	v_mul_f32_e32 v113, v113, v113
	v_fmac_f32_e32 v83, v92, v92
	v_fmac_f32_e32 v84, v94, v94
	v_fmac_f32_e32 v117, v116, v116
	v_mul_f32_e32 v116, v119, v119
	v_fmac_f32_e32 v113, v112, v112
	v_mul_f32_e32 v112, v115, v115
	v_add_f32_e32 v83, v83, v84
	v_mul_f32_e32 v84, v89, v89
	v_mul_f32_e32 v85, v91, v91
	v_fmac_f32_e32 v116, v118, v118
	v_fmac_f32_e32 v112, v114, v114
	v_fmac_f32_e32 v84, v88, v88
	v_fmac_f32_e32 v85, v90, v90
	v_add_f32_e32 v116, v117, v116
	v_add_f32_e32 v112, v113, v112
	v_add_f32_e32 v84, v84, v85
	v_add_f32_e32 v112, v116, v112
	v_add_f32_e32 v83, v83, v84
	v_add_f32_e32 v85, v112, v83
	ds_bpermute_b32 v86, v237, v85
	v_mul_f32_e32 v80, v44, v92
	v_mul_f32_e32 v81, v45, v93
	v_cvt_pk_bf16_f32 v82, v80, v81
	v_mul_f32_e32 v80, v46, v94
	v_mul_f32_e32 v81, v47, v95
	v_cvt_pk_bf16_f32 v83, v80, v81
	v_mul_f32_e32 v80, v40, v88
	v_mul_f32_e32 v81, v41, v89
	v_cvt_pk_bf16_f32 v84, v80, v81
	s_waitcnt lgkmcnt(0)
	v_add_f32_e32 v80, v85, v86
	ds_bpermute_b32 v81, v236, v80
	v_mul_f32_e32 v85, v42, v90
	v_mul_f32_e32 v86, v43, v91
	v_cvt_pk_bf16_f32 v85, v85, v86
	global_store_dwordx4 v[122:123], v[82:85], off offset:256
	s_and_saveexec_b64 s[0:1], s[4:5]
	s_cbranch_execz .LBB0_565
	v_readlane_b32 s24, v253, 23
	v_lshlrev_b64 v[82:83], 6, v[120:121]
	v_readlane_b32 s25, v253, 24
	s_lshl_b32 s16, s53, 2
	s_waitcnt lgkmcnt(0)
	v_add_f32_e32 v80, v80, v81
	v_lshl_add_u64 v[82:83], s[24:25], 0, v[82:83]
	v_lshl_add_u64 v[82:83], s[22:23], 2, v[82:83]
	v_lshl_add_u64 v[82:83], v[82:83], 0, s[16:17]
	global_store_dword v[82:83], v80, off

; __device__ __forceinline__ float bflo(unsigned w) { return __uint_as_float(w << 16); }
; __device__ __forceinline__ float bfhi(unsigned w) { return __uint_as_float(w & 0xffff0000u); }
;   __device__ __forceinline__ void operator()(const f32x4 (&acc)[2][2][4][2], const Unit& u, int wr, int wc, int fr, int fq) const {
;     ...
;         const int row = row0 + ai * PG_HALF + m * 16;
;         u16* op = (u16*)(p->ws + OFF_XS) + (size_t)row * 1024 + col0;
;         u16* hp = Hout + (size_t)row * 1024 + col0;
;         float sq = 0.f;
; #pragma unroll
;         for (int bj = 0; bj < 2; ++bj) {
;           float x[8], rr[8];
;           if (first) {
;             const float* rp = resid_row(*p, true, row) + col0;
;             const float4 r0 = *(const float4*)(rp + bj * PG_HALF), r1 = *(const float4*)(rp + bj * PG_HALF + 4);
;             rr[0] = r0.x; rr[1] = r0.y; rr[2] = r0.z; rr[3] = r0.w; rr[4] = r1.x; rr[5] = r1.y; rr[6] = r1.z; rr[7] = r1.w;
;           } else {
;             const u32x4 rw = rwq[aim][m - mb][bj];
; #pragma unroll
;             for (int q = 0; q < 4; ++q) { rr[q * 2] = bflo(rw[q]); rr[q * 2 + 1] = bfhi(rw[q]); }
;           }
; #pragma unroll
;           for (int n = 0; n < 2; ++n) {
;             const float4 g = gq[bj][n];
;             const f32x4 a = acc[ai][bj][m][n];
;             x[n * 4 + 0] = rr[n * 4 + 0] + g.x * a[0]; x[n * 4 + 1] = rr[n * 4 + 1] + g.y * a[1]; x[n * 4 + 2] = rr[n * 4 + 2] + g.z * a[2]; x[n * 4 + 3] = rr[n * 4 + 3] + g.w * a[3];
;           }
;           { u32x4 xw = {cvtpk(x[0], x[1]), cvtpk(x[2], x[3]), cvtpk(x[4], x[5]), cvtpk(x[6], x[7])}; *(u32x4*)(op + bj * PG_HALF) = xw; }
;           if (emit) {
;             const float4 g0 = gmq[bj][0], g1 = gmq[bj][1];
;             sq += ((x[0] * x[0] + x[1] * x[1]) + (x[2] * x[2] + x[3] * x[3])) + ((x[4] * x[4] + x[5] * x[5]) + (x[6] * x[6] + x[7] * x[7]));
;             u32x4 w = {cvtpk(x[0] * g0.x, x[1] * g0.y), cvtpk(x[2] * g0.z, x[3] * g0.w), cvtpk(x[4] * g1.x, x[5] * g1.y), cvtpk(x[6] * g1.z, x[7] * g1.w)};
;             *(u32x4*)(hp + bj * PG_HALF) = w;
.LBB0_569:
	v_lshlrev_b64 v[90:91], 11, v[88:89]
	v_lshl_add_u64 v[92:93], s[86:87], 0, v[90:91]
	v_lshl_add_u64 v[92:93], v[92:93], 0, v[196:197]
	s_cmp_lg_u64 s[82:83], 0
	s_cbranch_scc1 .Lepw_19
	s_waitcnt vmcnt(1)
.Lepw_19:
	v_fmac_f32_e32 v84, v64, v76
	v_fmac_f32_e32 v85, v65, v77
	v_fmac_f32_e32 v86, v66, v78
	v_fmac_f32_e32 v87, v67, v79
	s_cmp_lg_u64 s[82:83], 0
	s_cbranch_scc1 .Lepw_20
	s_waitcnt vmcnt(0)
.Lepw_20:
	v_fmac_f32_e32 v80, v56, v72
	s_waitcnt lgkmcnt(0)
	v_fmac_f32_e32 v81, v57, v73
	v_cvt_pk_bf16_f32 v56, v84, v85
	v_cvt_pk_bf16_f32 v57, v86, v87
	v_fmac_f32_e32 v82, v58, v74
	v_fmac_f32_e32 v83, v59, v75
	v_cvt_pk_bf16_f32 v58, v80, v81
	v_cvt_pk_bf16_f32 v59, v82, v83
	global_store_dwordx4 v[92:93], v[56:59], off
	v_lshl_add_u64 v[90:91], s[12:13], 0, v[90:91]
	v_lshl_add_u64 v[90:91], v[90:91], 0, v[196:197]
	v_mul_f32_e32 v56, v68, v84
	v_mul_f32_e32 v57, v69, v85
	v_cvt_pk_bf16_f32 v56, v56, v57
	v_mul_f32_e32 v57, v70, v86
	v_mul_f32_e32 v58, v71, v87
	v_cvt_pk_bf16_f32 v57, v57, v58
	v_mul_f32_e32 v58, v60, v80
	v_mul_f32_e32 v59, v61, v81
	v_cvt_pk_bf16_f32 v58, v58, v59
	v_mul_f32_e32 v59, v62, v82
	v_mul_f32_e32 v64, v63, v83
	v_cvt_pk_bf16_f32 v59, v59, v64
	s_and_b64 vcc, exec, s[8:9]
	s_mov_b64 s[24:25], -1
	global_store_dwordx4 v[90:91], v[56:59], off
	s_cbranch_vccnz .LBB0_571
	v_lshlrev_b32_e32 v64, 16, v128
	v_and_b32_e32 v65, 0xffff0000, v128
	v_lshlrev_b32_e32 v66, 16, v129
	v_and_b32_e32 v67, 0xffff0000, v129
	v_lshlrev_b32_e32 v56, 16, v130
	v_and_b32_e32 v57, 0xffff0000, v130
	v_lshlrev_b32_e32 v58, 16, v131
	v_and_b32_e32 v59, 0xffff0000, v131
	s_mov_b64 s[24:25], 0

; __device__ __forceinline__ float bflo(unsigned w) { return __uint_as_float(w << 16); }
; __device__ __forceinline__ float bfhi(unsigned w) { return __uint_as_float(w & 0xffff0000u); }
;   __device__ __forceinline__ void operator()(const f32x4 (&acc)[2][2][4][2], const Unit& u, int wr, int wc, int fr, int fq) const {
;     ...
;         for (int bj = 0; bj < 2; ++bj) {
;           float x[8], rr[8];
;           if (first) {
;             const float* rp = resid_row(*p, true, row) + col0;
;             const float4 r0 = *(const float4*)(rp + bj * PG_HALF), r1 = *(const float4*)(rp + bj * PG_HALF + 4);
;             rr[0] = r0.x; rr[1] = r0.y; rr[2] = r0.z; rr[3] = r0.w; rr[4] = r1.x; rr[5] = r1.y; rr[6] = r1.z; rr[7] = r1.w;
;           } else {
;             const u32x4 rw = rwq[aim][m - mb][bj];
; #pragma unroll
;             for (int q = 0; q < 4; ++q) { rr[q * 2] = bflo(rw[q]); rr[q * 2 + 1] = bfhi(rw[q]); }
;           }
; #pragma unroll
;           for (int n = 0; n < 2; ++n) {
;             const float4 g = gq[bj][n];
;             const f32x4 a = acc[ai][bj][m][n];
;             x[n * 4 + 0] = rr[n * 4 + 0] + g.x * a[0]; x[n * 4 + 1] = rr[n * 4 + 1] + g.y * a[1]; x[n * 4 + 2] = rr[n * 4 + 2] + g.z * a[2]; x[n * 4 + 3] = rr[n * 4 + 3] + g.w * a[3];
;           }
;           { u32x4 xw = {cvtpk(x[0], x[1]), cvtpk(x[2], x[3]), cvtpk(x[4], x[5]), cvtpk(x[6], x[7])}; *(u32x4*)(op + bj * PG_HALF) = xw; }
;           if (emit) {
;             const float4 g0 = gmq[bj][0], g1 = gmq[bj][1];
;             sq += ((x[0] * x[0] + x[1] * x[1]) + (x[2] * x[2] + x[3] * x[3])) + ((x[4] * x[4] + x[5] * x[5]) + (x[6] * x[6] + x[7] * x[7]));
;             u32x4 w = {cvtpk(x[0] * g0.x, x[1] * g0.y), cvtpk(x[2] * g0.z, x[3] * g0.w), cvtpk(x[4] * g1.x, x[5] * g1.y), cvtpk(x[6] * g1.z, x[7] * g1.w)};
;             *(u32x4*)(hp + bj * PG_HALF) = w;
;           }
;         }
;         if (emit) {
;           sq += __int_as_float(__builtin_amdgcn_ds_bpermute((lane ^ 16) << 2, __float_as_int(sq)));
;           sq += __int_as_float(__builtin_amdgcn_ds_bpermute((lane ^ 32) << 2, __float_as_int(sq)));
;           if (fq == 0) ssq[(size_t)row * 16 + u.pn * 4 + wc] = sq;
.Lepw_21:
	v_fmac_f32_e32 v65, v37, v53
	v_fmac_f32_e32 v67, v39, v55
	s_cmp_lg_u64 s[82:83], 0
	s_cbranch_scc1 .Lepw_22
	s_waitcnt vmcnt(0)
.Lepw_22:
	v_fmac_f32_e32 v58, v34, v50
	v_fmac_f32_e32 v59, v35, v51
	v_cvt_pk_bf16_f32 v35, v58, v59
	v_fmac_f32_e32 v64, v36, v52
	v_fmac_f32_e32 v66, v38, v54
	v_fmac_f32_e32 v56, v32, v48
	v_fmac_f32_e32 v57, v33, v49
	v_cvt_pk_bf16_f32 v32, v64, v65
	v_cvt_pk_bf16_f32 v33, v66, v67
	v_cvt_pk_bf16_f32 v34, v56, v57
	global_store_dwordx4 v[92:93], v[32:35], off offset:256
	v_mul_f32_e32 v36, v67, v67
	v_mul_f32_e32 v85, v85, v85
	v_mul_f32_e32 v35, v65, v65
	v_mul_f32_e32 v81, v81, v81
	v_fmac_f32_e32 v35, v64, v64
	v_fmac_f32_e32 v36, v66, v66
	v_fmac_f32_e32 v85, v84, v84
	v_mul_f32_e32 v84, v87, v87
	v_fmac_f32_e32 v81, v80, v80
	v_mul_f32_e32 v80, v83, v83
	v_add_f32_e32 v35, v35, v36
	v_mul_f32_e32 v36, v57, v57
	v_mul_f32_e32 v37, v59, v59
	v_fmac_f32_e32 v84, v86, v86
	v_fmac_f32_e32 v80, v82, v82
	v_fmac_f32_e32 v36, v56, v56
	v_fmac_f32_e32 v37, v58, v58
	v_add_f32_e32 v84, v85, v84
	v_add_f32_e32 v80, v81, v80
	v_add_f32_e32 v36, v36, v37
	v_add_f32_e32 v80, v84, v80
	v_add_f32_e32 v35, v35, v36
	v_add_f32_e32 v37, v80, v35
	ds_bpermute_b32 v38, v237, v37
	v_mul_f32_e32 v32, v44, v64
	v_mul_f32_e32 v33, v45, v65
	v_cvt_pk_bf16_f32 v34, v32, v33
	v_mul_f32_e32 v32, v46, v66
	v_mul_f32_e32 v33, v47, v67
	v_cvt_pk_bf16_f32 v35, v32, v33
	v_mul_f32_e32 v32, v40, v56
	v_mul_f32_e32 v33, v41, v57
	v_cvt_pk_bf16_f32 v36, v32, v33
	s_waitcnt lgkmcnt(0)
	v_add_f32_e32 v32, v37, v38
	ds_bpermute_b32 v33, v236, v32
	v_mul_f32_e32 v37, v42, v58
	v_mul_f32_e32 v38, v43, v59
	v_cvt_pk_bf16_f32 v37, v37, v38
	global_store_dwordx4 v[90:91], v[34:37], off offset:256
	s_and_saveexec_b64 s[0:1], s[4:5]
	s_cbranch_execz .LBB0_575
	v_readlane_b32 s24, v253, 23
	v_lshlrev_b64 v[34:35], 6, v[88:89]
	v_readlane_b32 s25, v253, 24
	s_lshl_b32 s16, s53, 2
	s_waitcnt lgkmcnt(0)
	v_add_f32_e32 v32, v32, v33
	v_lshl_add_u64 v[34:35], s[24:25], 0, v[34:35]
	v_lshl_add_u64 v[34:35], s[22:23], 2, v[34:35]
	v_lshl_add_u64 v[34:35], v[34:35], 0, s[16:17]
	global_store_dword v[34:35], v32, off
.LBB0_575:
	s_or_b64 exec, exec, s[0:1]
	s_movk_i32 s0, 0x7f60
	v_cmp_gt_i32_e64 s[0:1], s0, v222
	s_and_b64 vcc, exec, s[8:9]
	s_mov_b64 s[24:25], -1
	s_cbranch_vccnz .LBB0_577
	s_waitcnt vmcnt(0)
	v_lshlrev_b32_e32 v36, 16, v108
	v_and_b32_e32 v37, 0xffff0000, v108
	v_lshlrev_b32_e32 v38, 16, v109
	v_and_b32_e32 v39, 0xffff0000, v109
	v_lshlrev_b32_e32 v32, 16, v110
	s_waitcnt lgkmcnt(0)
	v_and_b32_e32 v33, 0xffff0000, v110
	v_lshlrev_b32_e32 v34, 16, v111
	v_and_b32_e32 v35, 0xffff0000, v111
	s_mov_b64 s[24:25], 0

; __device__ __forceinline__ float bflo(unsigned w) { return __uint_as_float(w << 16); }
; __device__ __forceinline__ float bfhi(unsigned w) { return __uint_as_float(w & 0xffff0000u); }
;   __device__ __forceinline__ void operator()(const f32x4 (&acc)[2][2][4][2], const Unit& u, int wr, int wc, int fr, int fq) const {
;     ...
;         const int row = row0 + ai * PG_HALF + m * 16;
;         u16* op = (u16*)(p->ws + OFF_XS) + (size_t)row * 1024 + col0;
;         u16* hp = Hout + (size_t)row * 1024 + col0;
;         float sq = 0.f;
; #pragma unroll
;         for (int bj = 0; bj < 2; ++bj) {
;           float x[8], rr[8];
;           if (first) {
;             const float* rp = resid_row(*p, true, row) + col0;
;             const float4 r0 = *(const float4*)(rp + bj * PG_HALF), r1 = *(const float4*)(rp + bj * PG_HALF + 4);
;             rr[0] = r0.x; rr[1] = r0.y; rr[2] = r0.z; rr[3] = r0.w; rr[4] = r1.x; rr[5] = r1.y; rr[6] = r1.z; rr[7] = r1.w;
;           } else {
;             const u32x4 rw = rwq[aim][m - mb][bj];
; #pragma unroll
;             for (int q = 0; q < 4; ++q) { rr[q * 2] = bflo(rw[q]); rr[q * 2 + 1] = bfhi(rw[q]); }
;           }
; #pragma unroll
;           for (int n = 0; n < 2; ++n) {
;             const float4 g = gq[bj][n];
;             const f32x4 a = acc[ai][bj][m][n];
;             x[n * 4 + 0] = rr[n * 4 + 0] + g.x * a[0]; x[n * 4 + 1] = rr[n * 4 + 1] + g.y * a[1]; x[n * 4 + 2] = rr[n * 4 + 2] + g.z * a[2]; x[n * 4 + 3] = rr[n * 4 + 3] + g.w * a[3];
;           }
;           { u32x4 xw = {cvtpk(x[0], x[1]), cvtpk(x[2], x[3]), cvtpk(x[4], x[5]), cvtpk(x[6], x[7])}; *(u32x4*)(op + bj * PG_HALF) = xw; }
;           if (emit) {
;             const float4 g0 = gmq[bj][0], g1 = gmq[bj][1];
;             sq += ((x[0] * x[0] + x[1] * x[1]) + (x[2] * x[2] + x[3] * x[3])) + ((x[4] * x[4] + x[5] * x[5]) + (x[6] * x[6] + x[7] * x[7]));
;             u32x4 w = {cvtpk(x[0] * g0.x, x[1] * g0.y), cvtpk(x[2] * g0.z, x[3] * g0.w), cvtpk(x[4] * g1.x, x[5] * g1.y), cvtpk(x[6] * g1.z, x[7] * g1.w)};
;             *(u32x4*)(hp + bj * PG_HALF) = w;
.LBB0_579:
	v_lshlrev_b64 v[58:59], 11, v[56:57]
	v_lshl_add_u64 v[64:65], s[86:87], 0, v[58:59]
	v_lshl_add_u64 v[64:65], v[64:65], 0, v[196:197]
	s_cmp_lg_u64 s[82:83], 0
	s_cbranch_scc1 .Lepw_23
	s_waitcnt vmcnt(1)
.Lepw_23:
	v_fmac_f32_e32 v36, v28, v76
	v_fmac_f32_e32 v37, v29, v77
	v_fmac_f32_e32 v38, v30, v78
	v_fmac_f32_e32 v39, v31, v79
	s_cmp_lg_u64 s[82:83], 0
	s_cbranch_scc1 .Lepw_24
	s_waitcnt vmcnt(0)
.Lepw_24:
	v_fmac_f32_e32 v32, v24, v72
	s_waitcnt lgkmcnt(0)
	v_fmac_f32_e32 v33, v25, v73
	v_cvt_pk_bf16_f32 v24, v36, v37
	v_cvt_pk_bf16_f32 v25, v38, v39
	v_fmac_f32_e32 v34, v26, v74
	v_fmac_f32_e32 v35, v27, v75
	v_cvt_pk_bf16_f32 v26, v32, v33
	v_cvt_pk_bf16_f32 v27, v34, v35
	global_store_dwordx4 v[64:65], v[24:27], off
	v_lshl_add_u64 v[58:59], s[12:13], 0, v[58:59]
	v_lshl_add_u64 v[58:59], v[58:59], 0, v[196:197]
	v_mul_f32_e32 v24, v68, v36
	v_mul_f32_e32 v25, v69, v37
	v_cvt_pk_bf16_f32 v24, v24, v25
	v_mul_f32_e32 v25, v70, v38
	v_mul_f32_e32 v26, v71, v39
	v_cvt_pk_bf16_f32 v25, v25, v26
	v_mul_f32_e32 v26, v60, v32
	v_mul_f32_e32 v27, v61, v33
	v_cvt_pk_bf16_f32 v26, v26, v27
	v_mul_f32_e32 v27, v62, v34
	v_mul_f32_e32 v28, v63, v35
	v_cvt_pk_bf16_f32 v27, v27, v28
	s_and_b64 vcc, exec, s[8:9]
	s_mov_b64 s[24:25], -1
	global_store_dwordx4 v[58:59], v[24:27], off
	s_cbranch_vccnz .LBB0_581
	v_lshlrev_b32_e32 v28, 16, v104
	v_and_b32_e32 v29, 0xffff0000, v104
	v_lshlrev_b32_e32 v30, 16, v105
	v_and_b32_e32 v31, 0xffff0000, v105
	v_lshlrev_b32_e32 v24, 16, v106
	v_and_b32_e32 v25, 0xffff0000, v106
	v_lshlrev_b32_e32 v26, 16, v107
	v_and_b32_e32 v27, 0xffff0000, v107
	s_mov_b64 s[24:25], 0

;   __device__ __forceinline__ void operator()(const f32x4 (&acc)[2][2][4][2], const Unit& u, int wr, int wc, int fr, int fq) const {
;     ...
; #pragma unroll
;           for (int n = 0; n < 2; ++n) {
;             const float4 g = gq[bj][n];
;             const f32x4 a = acc[ai][bj][m][n];
;             x[n * 4 + 0] = rr[n * 4 + 0] + g.x * a[0]; x[n * 4 + 1] = rr[n * 4 + 1] + g.y * a[1]; x[n * 4 + 2] = rr[n * 4 + 2] + g.z * a[2]; x[n * 4 + 3] = rr[n * 4 + 3] + g.w * a[3];
;           }
;           { u32x4 xw = {cvtpk(x[0], x[1]), cvtpk(x[2], x[3]), cvtpk(x[4], x[5]), cvtpk(x[6], x[7])}; *(u32x4*)(op + bj * PG_HALF) = xw; }
;           if (emit) {
;             const float4 g0 = gmq[bj][0], g1 = gmq[bj][1];
;             sq += ((x[0] * x[0] + x[1] * x[1]) + (x[2] * x[2] + x[3] * x[3])) + ((x[4] * x[4] + x[5] * x[5]) + (x[6] * x[6] + x[7] * x[7]));
;             u32x4 w = {cvtpk(x[0] * g0.x, x[1] * g0.y), cvtpk(x[2] * g0.z, x[3] * g0.w), cvtpk(x[4] * g1.x, x[5] * g1.y), cvtpk(x[6] * g1.z, x[7] * g1.w)};
;             *(u32x4*)(hp + bj * PG_HALF) = w;
;           }
;         }
;         if (emit) {
;           sq += __int_as_float(__builtin_amdgcn_ds_bpermute((lane ^ 16) << 2, __float_as_int(sq)));
;           sq += __int_as_float(__builtin_amdgcn_ds_bpermute((lane ^ 32) << 2, __float_as_int(sq)));
;           if (fq == 0) ssq[(size_t)row * 16 + u.pn * 4 + wc] = sq;
.Lepw_25:
	v_fmac_f32_e32 v29, v21, v53
	v_fmac_f32_e32 v31, v23, v55
	s_cmp_lg_u64 s[82:83], 0
	s_cbranch_scc1 .Lepw_26
	s_waitcnt vmcnt(0)
.Lepw_26:
	v_fmac_f32_e32 v26, v18, v50
	v_fmac_f32_e32 v27, v19, v51
	v_cvt_pk_bf16_f32 v19, v26, v27
	v_fmac_f32_e32 v28, v20, v52
	v_fmac_f32_e32 v30, v22, v54
	v_fmac_f32_e32 v24, v16, v48
	v_fmac_f32_e32 v25, v17, v49
	v_cvt_pk_bf16_f32 v16, v28, v29
	v_cvt_pk_bf16_f32 v17, v30, v31
	v_cvt_pk_bf16_f32 v18, v24, v25
	global_store_dwordx4 v[64:65], v[16:19], off offset:256
	v_mul_f32_e32 v20, v31, v31
	v_mul_f32_e32 v37, v37, v37
	v_mul_f32_e32 v19, v29, v29
	v_mul_f32_e32 v33, v33, v33
	v_fmac_f32_e32 v19, v28, v28
	v_fmac_f32_e32 v20, v30, v30
	v_fmac_f32_e32 v37, v36, v36
	v_mul_f32_e32 v36, v39, v39
	v_fmac_f32_e32 v33, v32, v32
	v_mul_f32_e32 v32, v35, v35
	v_add_f32_e32 v19, v19, v20
	v_mul_f32_e32 v20, v25, v25
	v_mul_f32_e32 v21, v27, v27
	v_fmac_f32_e32 v36, v38, v38
	v_fmac_f32_e32 v32, v34, v34
	v_fmac_f32_e32 v20, v24, v24
	v_fmac_f32_e32 v21, v26, v26
	v_add_f32_e32 v36, v37, v36
	v_add_f32_e32 v32, v33, v32
	v_add_f32_e32 v20, v20, v21
	v_add_f32_e32 v32, v36, v32
	v_add_f32_e32 v19, v19, v20
	v_add_f32_e32 v21, v32, v19
	ds_bpermute_b32 v22, v237, v21
	v_mul_f32_e32 v16, v44, v28
	v_mul_f32_e32 v17, v45, v29
	v_cvt_pk_bf16_f32 v18, v16, v17
	v_mul_f32_e32 v16, v46, v30
	v_mul_f32_e32 v17, v47, v31
	v_cvt_pk_bf16_f32 v19, v16, v17
	v_mul_f32_e32 v16, v40, v24
	v_mul_f32_e32 v17, v41, v25
	v_cvt_pk_bf16_f32 v20, v16, v17
	s_waitcnt lgkmcnt(0)
	v_add_f32_e32 v16, v21, v22
	ds_bpermute_b32 v17, v236, v16
	v_mul_f32_e32 v21, v42, v26
	v_mul_f32_e32 v22, v43, v27
	v_cvt_pk_bf16_f32 v21, v21, v22
	global_store_dwordx4 v[58:59], v[18:21], off offset:256
	s_and_saveexec_b64 s[0:1], s[4:5]
	s_cbranch_execz .LBB0_585
	v_readlane_b32 s24, v253, 23
	v_lshlrev_b64 v[18:19], 6, v[56:57]
	v_readlane_b32 s25, v253, 24
	s_lshl_b32 s16, s53, 2
	s_waitcnt lgkmcnt(0)
	v_add_f32_e32 v16, v16, v17
	v_lshl_add_u64 v[18:19], s[24:25], 0, v[18:19]
	v_lshl_add_u64 v[18:19], s[22:23], 2, v[18:19]
	v_lshl_add_u64 v[18:19], v[18:19], 0, s[16:17]
	global_store_dword v[18:19], v16, off

; __device__ __forceinline__ float bflo(unsigned w) { return __uint_as_float(w << 16); }
; __device__ __forceinline__ float bfhi(unsigned w) { return __uint_as_float(w & 0xffff0000u); }
;   __device__ __forceinline__ void operator()(const f32x4 (&acc)[2][2][4][2], const Unit& u, int wr, int wc, int fr, int fq) const {
;     ...
;         const int row = row0 + ai * PG_HALF + m * 16;
;         u16* op = (u16*)(p->ws + OFF_XS) + (size_t)row * 1024 + col0;
;         u16* hp = Hout + (size_t)row * 1024 + col0;
;         float sq = 0.f;
; #pragma unroll
;         for (int bj = 0; bj < 2; ++bj) {
;           float x[8], rr[8];
;           if (first) {
;             const float* rp = resid_row(*p, true, row) + col0;
;             const float4 r0 = *(const float4*)(rp + bj * PG_HALF), r1 = *(const float4*)(rp + bj * PG_HALF + 4);
;             rr[0] = r0.x; rr[1] = r0.y; rr[2] = r0.z; rr[3] = r0.w; rr[4] = r1.x; rr[5] = r1.y; rr[6] = r1.z; rr[7] = r1.w;
;           } else {
;             const u32x4 rw = rwq[aim][m - mb][bj];
; #pragma unroll
;             for (int q = 0; q < 4; ++q) { rr[q * 2] = bflo(rw[q]); rr[q * 2 + 1] = bfhi(rw[q]); }
;           }
; #pragma unroll
;           for (int n = 0; n < 2; ++n) {
;             const float4 g = gq[bj][n];
;             const f32x4 a = acc[ai][bj][m][n];
;             x[n * 4 + 0] = rr[n * 4 + 0] + g.x * a[0]; x[n * 4 + 1] = rr[n * 4 + 1] + g.y * a[1]; x[n * 4 + 2] = rr[n * 4 + 2] + g.z * a[2]; x[n * 4 + 3] = rr[n * 4 + 3] + g.w * a[3];
;           }
;           { u32x4 xw = {cvtpk(x[0], x[1]), cvtpk(x[2], x[3]), cvtpk(x[4], x[5]), cvtpk(x[6], x[7])}; *(u32x4*)(op + bj * PG_HALF) = xw; }
;           if (emit) {
;             const float4 g0 = gmq[bj][0], g1 = gmq[bj][1];
;             sq += ((x[0] * x[0] + x[1] * x[1]) + (x[2] * x[2] + x[3] * x[3])) + ((x[4] * x[4] + x[5] * x[5]) + (x[6] * x[6] + x[7] * x[7]));
;             u32x4 w = {cvtpk(x[0] * g0.x, x[1] * g0.y), cvtpk(x[2] * g0.z, x[3] * g0.w), cvtpk(x[4] * g1.x, x[5] * g1.y), cvtpk(x[6] * g1.z, x[7] * g1.w)};
;             *(u32x4*)(hp + bj * PG_HALF) = w;
.LBB0_589:
	v_lshlrev_b64 v[26:27], 11, v[24:25]
	v_lshl_add_u64 v[28:29], s[86:87], 0, v[26:27]
	v_lshl_add_u64 v[28:29], v[28:29], 0, v[196:197]
	s_cmp_lg_u64 s[82:83], 0
	s_cbranch_scc1 .Lepw_27
	s_waitcnt vmcnt(1)
.Lepw_27:
	v_fmac_f32_e32 v20, v12, v76
	v_fmac_f32_e32 v21, v13, v77
	v_fmac_f32_e32 v22, v14, v78
	v_fmac_f32_e32 v23, v15, v79
	s_cmp_lg_u64 s[82:83], 0
	s_cbranch_scc1 .Lepw_28
	s_waitcnt vmcnt(0)
.Lepw_28:
	v_fmac_f32_e32 v16, v8, v72
	s_waitcnt lgkmcnt(0)
	v_fmac_f32_e32 v17, v9, v73
	v_cvt_pk_bf16_f32 v8, v20, v21
	v_cvt_pk_bf16_f32 v9, v22, v23
	v_fmac_f32_e32 v18, v10, v74
	v_fmac_f32_e32 v19, v11, v75
	v_cvt_pk_bf16_f32 v10, v16, v17
	v_cvt_pk_bf16_f32 v11, v18, v19
	global_store_dwordx4 v[28:29], v[8:11], off
	v_lshl_add_u64 v[26:27], s[12:13], 0, v[26:27]
	v_lshl_add_u64 v[26:27], v[26:27], 0, v[196:197]
	v_mul_f32_e32 v8, v68, v20
	v_mul_f32_e32 v9, v69, v21
	v_cvt_pk_bf16_f32 v8, v8, v9
	v_mul_f32_e32 v9, v70, v22
	v_mul_f32_e32 v10, v71, v23
	v_cvt_pk_bf16_f32 v9, v9, v10
	v_mul_f32_e32 v10, v60, v16
	v_mul_f32_e32 v11, v61, v17
	v_cvt_pk_bf16_f32 v10, v10, v11
	v_mul_f32_e32 v11, v62, v18
	v_mul_f32_e32 v12, v63, v19
	v_cvt_pk_bf16_f32 v11, v11, v12
	s_and_b64 vcc, exec, s[8:9]
	s_mov_b64 s[8:9], -1
	global_store_dwordx4 v[26:27], v[8:11], off
	s_cbranch_vccnz .LBB0_591
	v_lshlrev_b32_e32 v12, 16, v96
	v_and_b32_e32 v13, 0xffff0000, v96
	v_lshlrev_b32_e32 v14, 16, v97
	v_and_b32_e32 v15, 0xffff0000, v97
	v_lshlrev_b32_e32 v8, 16, v98
	v_and_b32_e32 v9, 0xffff0000, v98
	v_lshlrev_b32_e32 v10, 16, v99
	v_and_b32_e32 v11, 0xffff0000, v99
	s_mov_b64 s[8:9], 0

;   __device__ __forceinline__ void operator()(const f32x4 (&acc)[2][2][4][2], const Unit& u, int wr, int wc, int fr, int fq) const {
;     ...
; #pragma unroll
;           for (int n = 0; n < 2; ++n) {
;             const float4 g = gq[bj][n];
;             const f32x4 a = acc[ai][bj][m][n];
;             x[n * 4 + 0] = rr[n * 4 + 0] + g.x * a[0]; x[n * 4 + 1] = rr[n * 4 + 1] + g.y * a[1]; x[n * 4 + 2] = rr[n * 4 + 2] + g.z * a[2]; x[n * 4 + 3] = rr[n * 4 + 3] + g.w * a[3];
;           }
;           { u32x4 xw = {cvtpk(x[0], x[1]), cvtpk(x[2], x[3]), cvtpk(x[4], x[5]), cvtpk(x[6], x[7])}; *(u32x4*)(op + bj * PG_HALF) = xw; }
;           if (emit) {
;             const float4 g0 = gmq[bj][0], g1 = gmq[bj][1];
;             sq += ((x[0] * x[0] + x[1] * x[1]) + (x[2] * x[2] + x[3] * x[3])) + ((x[4] * x[4] + x[5] * x[5]) + (x[6] * x[6] + x[7] * x[7]));
;             u32x4 w = {cvtpk(x[0] * g0.x, x[1] * g0.y), cvtpk(x[2] * g0.z, x[3] * g0.w), cvtpk(x[4] * g1.x, x[5] * g1.y), cvtpk(x[6] * g1.z, x[7] * g1.w)};
;             *(u32x4*)(hp + bj * PG_HALF) = w;
;           }
;         }
;         if (emit) {
;           sq += __int_as_float(__builtin_amdgcn_ds_bpermute((lane ^ 16) << 2, __float_as_int(sq)));
;           sq += __int_as_float(__builtin_amdgcn_ds_bpermute((lane ^ 32) << 2, __float_as_int(sq)));
;           if (fq == 0) ssq[(size_t)row * 16 + u.pn * 4 + wc] = sq;
.Lepw_29:
	v_fmac_f32_e32 v13, v5, v53
	v_fmac_f32_e32 v15, v7, v55
	s_cmp_lg_u64 s[82:83], 0
	s_cbranch_scc1 .Lepw_30
	s_waitcnt vmcnt(0)
.Lepw_30:
	v_fmac_f32_e32 v10, v2, v50
	v_fmac_f32_e32 v11, v3, v51
	v_cvt_pk_bf16_f32 v3, v10, v11
	v_fmac_f32_e32 v12, v4, v52
	v_fmac_f32_e32 v14, v6, v54
	v_fmac_f32_e32 v8, v0, v48
	v_fmac_f32_e32 v9, v1, v49
	v_cvt_pk_bf16_f32 v0, v12, v13
	v_cvt_pk_bf16_f32 v1, v14, v15
	v_cvt_pk_bf16_f32 v2, v8, v9
	global_store_dwordx4 v[28:29], v[0:3], off offset:256
	v_mul_f32_e32 v4, v15, v15
	v_mul_f32_e32 v21, v21, v21
	v_mul_f32_e32 v3, v13, v13
	v_mul_f32_e32 v17, v17, v17
	v_fmac_f32_e32 v3, v12, v12
	v_fmac_f32_e32 v4, v14, v14
	v_fmac_f32_e32 v21, v20, v20
	v_mul_f32_e32 v20, v23, v23
	v_fmac_f32_e32 v17, v16, v16
	v_mul_f32_e32 v16, v19, v19
	v_add_f32_e32 v3, v3, v4
	v_mul_f32_e32 v4, v9, v9
	v_mul_f32_e32 v5, v11, v11
	v_fmac_f32_e32 v20, v22, v22
	v_fmac_f32_e32 v16, v18, v18
	v_fmac_f32_e32 v4, v8, v8
	v_fmac_f32_e32 v5, v10, v10
	v_add_f32_e32 v20, v21, v20
	v_add_f32_e32 v16, v17, v16
	v_add_f32_e32 v4, v4, v5
	v_add_f32_e32 v16, v20, v16
	v_add_f32_e32 v3, v3, v4
	v_add_f32_e32 v5, v16, v3
	ds_bpermute_b32 v6, v237, v5
	v_mul_f32_e32 v0, v44, v12
	v_mul_f32_e32 v1, v45, v13
	v_cvt_pk_bf16_f32 v2, v0, v1
	v_mul_f32_e32 v0, v46, v14
	v_mul_f32_e32 v1, v47, v15
	v_cvt_pk_bf16_f32 v3, v0, v1
	v_mul_f32_e32 v0, v40, v8
	v_mul_f32_e32 v1, v41, v9
	v_cvt_pk_bf16_f32 v4, v0, v1
	s_waitcnt lgkmcnt(0)
	v_add_f32_e32 v0, v5, v6
	ds_bpermute_b32 v1, v236, v0
	v_mul_f32_e32 v5, v42, v10
	v_mul_f32_e32 v6, v43, v11
	v_cvt_pk_bf16_f32 v5, v5, v6
	global_store_dwordx4 v[26:27], v[2:5], off offset:256
	s_and_saveexec_b64 s[0:1], s[4:5]
	s_cbranch_execz .LBB0_494
	v_readlane_b32 s8, v253, 23
	v_lshlrev_b64 v[2:3], 6, v[24:25]
	v_readlane_b32 s9, v253, 24
	s_lshl_b32 s16, s53, 2
	s_waitcnt lgkmcnt(0)
	v_add_f32_e32 v0, v0, v1
	v_lshl_add_u64 v[2:3], s[8:9], 0, v[2:3]
	v_lshl_add_u64 v[2:3], s[22:23], 2, v[2:3]
	v_lshl_add_u64 v[2:3], v[2:3], 0, s[16:17]
	global_store_dword v[2:3], v0, off
	s_branch .LBB0_494
